# P1 row loop: four 8-byte H stores per row -> two 16-byte stores (DPP lane-pair exchange), no write-through
# baseline (speedup 1.0000x reference)
; __global__ void __launch_bounds__(NT, 2) fwd_kernel(Args args) {
;     ...
;         f32x4 gpre[4];
; #pragma unroll
;         for (int j = 0; j < 4; ++j) gpre[j] = *(const f32x4*)(g_mix_pre + 4 * (lane + 64 * j));
;         _Pragma("unroll 1") for (int grp = 0; grp < 3; ++grp) {
;             if (grp == 2 && wave >= 4) break;
;             const int nr = (grp < 2) ? 4 : 1, toff = (grp < 2) ? 0 : 2048;
.LBB0_99:
	v_and_b32_e32 v21, 63, v1
	v_lshlrev_b32_e32 v18, 4, v21
	s_waitcnt lgkmcnt(0)
	s_barrier
	s_mov_b32 s98, 0x55555555
	s_mov_b32 s99, 0x55555555
	v_and_b32_e32 v214, 1, v0
	v_mul_u32_u24_e32 v214, 0x1f8, v214
	v_mov_b32_e32 v215, 0
	global_load_dwordx4 v[2:5], v18, s[28:29]
	global_load_dwordx4 v[6:9], v18, s[28:29] offset:1024
	global_load_dwordx4 v[10:13], v18, s[28:29] offset:2048
	global_load_dwordx4 v[14:17], v18, s[28:29] offset:3072
	s_ashr_i32 s0, s0, 6
	s_cmp_gt_i32 s0, 3
	s_cselect_b64 s[6:7], -1, 0
	s_lshl_b32 s1, s2, 2
	s_lshl_b32 s3, s0, 3
	s_add_i32 s0, s0, s1
	s_ashr_i32 s1, s0, 31
	s_lshl_b32 s19, s2, 6
	s_lshl_b64 s[4:5], s[0:1], 12
	s_add_u32 s23, s20, s4
	v_lshlrev_b32_e32 v20, 2, v21
	s_addc_u32 s26, s21, s5
	s_add_i32 s14, s0, 0x4000
	v_lshl_add_u64 v[86:87], s[16:17], 0, v[18:19]
	v_add_u32_e32 v101, 0, v18
	v_lshlrev_b32_e32 v18, 3, v21
	v_xor_b32_e32 v1, 4, v20
	v_xor_b32_e32 v91, 8, v20
	v_xor_b32_e32 v93, 16, v20
	v_xor_b32_e32 v98, 32, v20
	v_xor_b32_e32 v99, 64, v20
	v_xor_b32_e32 v100, 0x80, v20
	s_ashr_i32 s15, s14, 31
	v_lshl_add_u64 v[88:89], s[76:77], 0, v[18:19]
	s_add_i32 s27, s19, s3
	v_lshlrev_b32_e32 v102, 2, v20
	v_mov_b32_e32 v90, 0x358637bd
	s_mov_b32 s18, 0x3a800000
	s_mov_b32 s28, 0x800000
	s_branch .LBB0_102

; #define LAS __attribute__((address_space(3)))
; __device__ __forceinline__ unsigned pk2(float lo, float hi) { const f32x2cv v = {lo, hi}; const bf16x2cv b = __builtin_convertvector(v, bf16x2cv); return __builtin_bit_cast(unsigned, b); }
; __device__ __forceinline__ float shx(float v, int o, int lane) { return __builtin_bit_cast(float, __builtin_amdgcn_ds_bpermute((lane ^ o) << 2, __builtin_bit_cast(int, v))); }
; __global__ void __launch_bounds__(NT, 2) fwd_kernel(Args args) {
;     ...
;             for (int q = 0; q < 4; ++q) { if (q < nr) { const int m = (grp < 2) ? 64 * bl + 8 * wave + 4 * grp + q : MLAT + 4 * bl + wave; float ss = 0.f;
; #pragma unroll
;                 for (int j = 0; j < 4; ++j) ss += (v[q][j].x * v[q][j].x + v[q][j].y * v[q][j].y) + (v[q][j].z * v[q][j].z + v[q][j].w * v[q][j].w);
; #pragma unroll
;                 for (int o = 1; o < 64; o <<= 1) ss += shx(ss, o, lane);
;                 const float rstd = rsqrtf(ss * (1.f / D) + EPS);
; #pragma unroll
;                 for (int j = 0; j < 4; ++j) { const int d0 = 4 * (lane + 64 * j); const f32x4 g = gpre[j];
;                     const f32x4 sh = *(LAS f32x4*)(T + toff + d0), sc = *(LAS f32x4*)(T + toff + 1024 + d0);
;                     const f32x4 h = (v[q][j] * rstd * g) * (sc + 1.0f) + sh;
;                     v2u w; w.x = pk2(h.x, h.y); w.y = pk2(h.z, h.w); *(v2u*)(H + (size_t)m * D + d0) = w; } } }
.LBB0_107:
	s_waitcnt vmcnt(3)
	v_pk_mul_f32 v[78:79], v[84:85], v[84:85]
	v_pk_mul_f32 v[80:81], v[82:83], v[82:83]
	s_waitcnt vmcnt(0)
	v_mul_f32_e32 v92, v66, v66
	v_pk_mov_b32 v[94:95], v[80:81], v[78:79] op_sel:[1,0]
	v_mov_b32_e32 v81, v79
	v_pk_add_f32 v[78:79], v[94:95], v[80:81]
	v_pk_mul_f32 v[80:81], v[76:77], v[76:77]
	v_pk_mul_f32 v[94:95], v[74:75], v[74:75]
	v_pk_add_f32 v[78:79], v[78:79], v[78:79] op_sel:[0,1] op_sel_hi:[1,0]
	v_pk_mov_b32 v[96:97], v[94:95], v[80:81] op_sel:[1,0]
	v_mov_b32_e32 v95, v81
	v_pk_add_f32 v[80:81], v[96:97], v[94:95]
	v_mul_f32_e32 v94, v67, v67
	v_pk_add_f32 v[80:81], v[80:81], v[80:81] op_sel:[0,1] op_sel_hi:[1,0]
	v_mov_b32_e32 v79, v92
	v_mov_b32_e32 v81, v94
	v_pk_add_f32 v[78:79], v[78:79], v[80:81]
	v_mul_f32_e32 v80, v71, v71
	v_mul_f32_e32 v95, v68, v68
	v_pk_fma_f32 v[80:81], v[70:71], v[70:71], v[80:81] op_sel_hi:[1,1,0]
	v_mul_f32_e32 v92, v73, v73
	v_mul_f32_e32 v96, v69, v69
	v_mov_b32_e32 v81, v95
	v_pk_fma_f32 v[94:95], v[72:73], v[72:73], v[92:93] op_sel_hi:[1,1,0]
	v_lshl_add_u32 v103, s3, 2, v101
	v_mov_b32_e32 v95, v96
	v_pk_add_f32 v[80:81], v[80:81], v[94:95]
	s_lshl_b64 s[0:1], s[0:1], 11
	v_pk_add_f32 v[78:79], v[78:79], v[80:81]
	s_nop 0
	v_add_f32_e32 v78, v78, v79
	ds_bpermute_b32 v79, v1, v78
	s_waitcnt lgkmcnt(0)
	v_add_f32_e32 v78, v78, v79
	ds_bpermute_b32 v79, v91, v78
	s_waitcnt lgkmcnt(0)
	v_add_f32_e32 v78, v78, v79
	ds_bpermute_b32 v79, v93, v78
	s_waitcnt lgkmcnt(0)
	v_add_f32_e32 v78, v78, v79
	ds_bpermute_b32 v79, v98, v78
	s_waitcnt lgkmcnt(0)
	v_add_f32_e32 v78, v78, v79
	ds_bpermute_b32 v79, v99, v78
	s_waitcnt lgkmcnt(0)
	v_add_f32_e32 v78, v78, v79
	ds_bpermute_b32 v79, v100, v78
	s_waitcnt lgkmcnt(0)
	v_add_f32_e32 v78, v78, v79
	v_fmamk_f32 v78, v78, 0x3a800000, v90
	v_mul_f32_e32 v79, 0x4b800000, v78
	v_cmp_gt_f32_e32 vcc, s28, v78
	s_nop 1
	v_cndmask_b32_e32 v78, v78, v79, vcc
	v_rsq_f32_e32 v92, v78
	ds_read_b128 v[78:81], v103
	ds_read_b128 v[104:107], v103 offset:4096
	ds_read_b128 v[108:111], v103 offset:5120
	v_mul_f32_e32 v94, 0x45800000, v92
	v_cndmask_b32_e32 v92, v92, v94, vcc
	v_pk_mul_f32 v[84:85], v[92:93], v[84:85] op_sel_hi:[0,1]
	v_pk_mul_f32 v[82:83], v[92:93], v[82:83] op_sel_hi:[0,1]
	v_pk_mul_f32 v[112:113], v[2:3], v[82:83]
	v_pk_mul_f32 v[114:115], v[4:5], v[84:85]
	ds_read_b128 v[82:85], v103 offset:1024
	s_waitcnt lgkmcnt(2)
	v_pk_add_f32 v[94:95], v[106:107], 1.0 op_sel_hi:[1,0]
	v_pk_add_f32 v[96:97], v[104:105], 1.0 op_sel_hi:[1,0]
	v_pk_fma_f32 v[104:105], v[94:95], v[114:115], v[80:81]
	v_pk_fma_f32 v[106:107], v[96:97], v[112:113], v[78:79]
	v_lshl_add_u64 v[112:113], v[88:89], 0, s[0:1]
	v_cvt_pk_bf16_f32 v200, v106, v107
	v_cvt_pk_bf16_f32 v201, v104, v105
	v_pk_mul_f32 v[76:77], v[92:93], v[76:77] op_sel_hi:[0,1]
	v_pk_mul_f32 v[74:75], v[92:93], v[74:75] op_sel_hi:[0,1]
	v_pk_mul_f32 v[104:105], v[6:7], v[74:75]
	v_pk_mul_f32 v[106:107], v[8:9], v[76:77]
	s_waitcnt lgkmcnt(1)
	v_pk_add_f32 v[74:75], v[110:111], 1.0 op_sel_hi:[1,0]
	v_pk_add_f32 v[76:77], v[108:109], 1.0 op_sel_hi:[1,0]
	s_waitcnt lgkmcnt(0)
	v_pk_fma_f32 v[106:107], v[74:75], v[106:107], v[84:85]
	v_pk_fma_f32 v[104:105], v[76:77], v[104:105], v[82:83]
	v_pk_mul_f32 v[72:73], v[92:93], v[72:73] op_sel_hi:[0,1]
	v_cvt_pk_bf16_f32 v202, v104, v105
	v_cvt_pk_bf16_f32 v203, v106, v107
	s_nop 1
	v_mov_b32_dpp v204, v200 quad_perm:[1,0,3,2] row_mask:0xf bank_mask:0xf
	v_mov_b32_dpp v205, v201 quad_perm:[1,0,3,2] row_mask:0xf bank_mask:0xf
	v_mov_b32_dpp v206, v202 quad_perm:[1,0,3,2] row_mask:0xf bank_mask:0xf
	v_mov_b32_dpp v207, v203 quad_perm:[1,0,3,2] row_mask:0xf bank_mask:0xf
	v_lshl_add_u64 v[212:213], v[112:113], 0, v[214:215]
	v_cndmask_b32_e64 v208, v206, v200, s[98:99]
	v_cndmask_b32_e64 v209, v207, v201, s[98:99]
	v_cndmask_b32_e64 v210, v202, v204, s[98:99]
	v_cndmask_b32_e64 v211, v203, v205, s[98:99]
	global_store_dwordx4 v[212:213], v[208:211], off
	ds_read_b128 v[104:107], v103 offset:2048
	ds_read_b128 v[108:111], v103 offset:6144
	v_pk_mul_f32 v[70:71], v[92:93], v[70:71] op_sel_hi:[0,1]
	v_pk_mul_f32 v[114:115], v[10:11], v[70:71]
	v_pk_mul_f32 v[116:117], v[12:13], v[72:73]
	ds_read_b128 v[70:73], v103 offset:7168
	s_waitcnt lgkmcnt(1)
	v_pk_add_f32 v[118:119], v[110:111], 1.0 op_sel_hi:[1,0]
	v_pk_add_f32 v[120:121], v[108:109], 1.0 op_sel_hi:[1,0]
	ds_read_b128 v[108:111], v103 offset:3072
	v_pk_mul_f32 v[68:69], v[92:93], v[68:69] op_sel_hi:[0,1]
	v_pk_mul_f32 v[66:67], v[92:93], v[66:67] op_sel_hi:[0,1]
	v_pk_mul_f32 v[66:67], v[14:15], v[66:67]
	v_pk_mul_f32 v[68:69], v[16:17], v[68:69]
	s_waitcnt lgkmcnt(1)
	v_pk_add_f32 v[72:73], v[72:73], 1.0 op_sel_hi:[1,0]
	v_pk_add_f32 v[70:71], v[70:71], 1.0 op_sel_hi:[1,0]
	v_pk_fma_f32 v[106:107], v[118:119], v[116:117], v[106:107]
	v_pk_fma_f32 v[104:105], v[120:121], v[114:115], v[104:105]
	s_waitcnt lgkmcnt(0)
	v_pk_fma_f32 v[68:69], v[72:73], v[68:69], v[110:111]
	v_pk_fma_f32 v[66:67], v[70:71], v[66:67], v[108:109]
	v_cvt_pk_bf16_f32 v200, v104, v105
	v_cvt_pk_bf16_f32 v201, v106, v107
	v_cvt_pk_bf16_f32 v202, v66, v67
	v_cvt_pk_bf16_f32 v203, v68, v69
	s_and_b64 vcc, exec, s[4:5]
	s_nop 1
	v_mov_b32_dpp v204, v200 quad_perm:[1,0,3,2] row_mask:0xf bank_mask:0xf
	v_mov_b32_dpp v205, v201 quad_perm:[1,0,3,2] row_mask:0xf bank_mask:0xf
	v_mov_b32_dpp v206, v202 quad_perm:[1,0,3,2] row_mask:0xf bank_mask:0xf
	v_mov_b32_dpp v207, v203 quad_perm:[1,0,3,2] row_mask:0xf bank_mask:0xf
	v_lshl_add_u64 v[212:213], v[112:113], 0, v[214:215]
	v_cndmask_b32_e64 v208, v206, v200, s[98:99]
	v_cndmask_b32_e64 v209, v207, v201, s[98:99]
	v_cndmask_b32_e64 v210, v202, v204, s[98:99]
	v_cndmask_b32_e64 v211, v203, v205, s[98:99]
	global_store_dwordx4 v[212:213], v[208:211], off offset:1024
	s_cbranch_vccnz .LBB0_100
; #define LAS __attribute__((address_space(3)))
; __device__ __forceinline__ unsigned pk2(float lo, float hi) { const f32x2cv v = {lo, hi}; const bf16x2cv b = __builtin_convertvector(v, bf16x2cv); return __builtin_bit_cast(unsigned, b); }
; __device__ __forceinline__ float shx(float v, int o, int lane) { return __builtin_bit_cast(float, __builtin_amdgcn_ds_bpermute((lane ^ o) << 2, __builtin_bit_cast(int, v))); }
; __global__ void __launch_bounds__(NT, 2) fwd_kernel(Args args) {
;     ...
;             for (int q = 0; q < 4; ++q) { if (q < nr) { const int m = (grp < 2) ? 64 * bl + 8 * wave + 4 * grp + q : MLAT + 4 * bl + wave; float ss = 0.f;
; #pragma unroll
;                 for (int j = 0; j < 4; ++j) ss += (v[q][j].x * v[q][j].x + v[q][j].y * v[q][j].y) + (v[q][j].z * v[q][j].z + v[q][j].w * v[q][j].w);
; #pragma unroll
;                 for (int o = 1; o < 64; o <<= 1) ss += shx(ss, o, lane);
;                 const float rstd = rsqrtf(ss * (1.f / D) + EPS);
; #pragma unroll
;                 for (int j = 0; j < 4; ++j) { const int d0 = 4 * (lane + 64 * j); const f32x4 g = gpre[j];
;                     const f32x4 sh = *(LAS f32x4*)(T + toff + d0), sc = *(LAS f32x4*)(T + toff + 1024 + d0);
;                     const f32x4 h = (v[q][j] * rstd * g) * (sc + 1.0f) + sh;
;                     v2u w; w.x = pk2(h.x, h.y); w.y = pk2(h.z, h.w); *(v2u*)(H + (size_t)m * D + d0) = w; } } }
	v_pk_mul_f32 v[66:67], v[20:21], v[20:21]
	v_pk_mul_f32 v[68:69], v[18:19], v[18:19]
	s_add_i32 s0, s20, 1
	v_pk_mov_b32 v[70:71], v[68:69], v[66:67] op_sel:[1,0]
	v_mov_b32_e32 v69, v67
	v_pk_add_f32 v[66:67], v[70:71], v[68:69]
	v_pk_mul_f32 v[68:69], v[24:25], v[24:25]
	v_pk_mul_f32 v[70:71], v[22:23], v[22:23]
	v_pk_add_f32 v[66:67], v[66:67], v[66:67] op_sel:[0,1] op_sel_hi:[1,0]
	v_pk_mov_b32 v[72:73], v[70:71], v[68:69] op_sel:[1,0]
	v_mov_b32_e32 v71, v69
	v_pk_add_f32 v[68:69], v[72:73], v[70:71]
	v_mul_f32_e32 v70, v38, v38
	v_mul_f32_e32 v71, v39, v39
	v_pk_add_f32 v[68:69], v[68:69], v[68:69] op_sel:[0,1] op_sel_hi:[1,0]
	v_mov_b32_e32 v67, v70
	v_mov_b32_e32 v69, v71
	v_pk_add_f32 v[66:67], v[66:67], v[68:69]
	v_mul_f32_e32 v68, v31, v31
	v_mul_f32_e32 v70, v33, v33
	v_mul_f32_e32 v72, v40, v40
	v_mul_f32_e32 v73, v41, v41
	v_pk_fma_f32 v[68:69], v[30:31], v[30:31], v[68:69] op_sel_hi:[1,1,0]
	v_pk_fma_f32 v[70:71], v[32:33], v[32:33], v[70:71] op_sel_hi:[1,1,0]
	v_mov_b32_e32 v69, v72
	v_mov_b32_e32 v71, v73
	v_pk_add_f32 v[68:69], v[68:69], v[70:71]
	s_ashr_i32 s1, s0, 31
	v_pk_add_f32 v[66:67], v[66:67], v[68:69]
	s_lshl_b64 s[0:1], s[0:1], 11
	v_add_f32_e32 v66, v66, v67
	ds_bpermute_b32 v67, v1, v66
	s_waitcnt lgkmcnt(0)
	v_add_f32_e32 v66, v66, v67
	ds_bpermute_b32 v67, v91, v66
	s_waitcnt lgkmcnt(0)
	v_add_f32_e32 v66, v66, v67
	ds_bpermute_b32 v67, v93, v66
	s_waitcnt lgkmcnt(0)
	v_add_f32_e32 v66, v66, v67
	ds_bpermute_b32 v67, v98, v66
	s_waitcnt lgkmcnt(0)
	v_add_f32_e32 v66, v66, v67
	ds_bpermute_b32 v67, v99, v66
	s_waitcnt lgkmcnt(0)
	v_add_f32_e32 v66, v66, v67
	ds_bpermute_b32 v67, v100, v66
	s_waitcnt lgkmcnt(0)
	v_add_f32_e32 v66, v66, v67
	v_fmamk_f32 v66, v66, 0x3a800000, v90
	v_mul_f32_e32 v67, 0x4b800000, v66
	v_cmp_gt_f32_e32 vcc, s28, v66
	s_nop 1
	v_cndmask_b32_e32 v66, v66, v67, vcc
	v_rsq_f32_e32 v66, v66
	s_nop 0
	v_mul_f32_e32 v67, 0x45800000, v66
	v_cndmask_b32_e32 v92, v66, v67, vcc
	v_pk_mul_f32 v[66:67], v[92:93], v[20:21] op_sel_hi:[0,1]
	v_pk_mul_f32 v[68:69], v[92:93], v[18:19] op_sel_hi:[0,1]
	v_pk_mul_f32 v[68:69], v[2:3], v[68:69]
	v_pk_mul_f32 v[66:67], v[4:5], v[66:67]
	v_pk_fma_f32 v[68:69], v[96:97], v[68:69], v[78:79]
	v_pk_fma_f32 v[66:67], v[94:95], v[66:67], v[80:81]
	v_pk_mul_f32 v[94:95], v[28:29], v[28:29]
	v_pk_mul_f32 v[96:97], v[26:27], v[26:27]
	v_cvt_pk_bf16_f32 v200, v68, v69
	v_pk_mov_b32 v[104:105], v[96:97], v[94:95] op_sel:[1,0]
	v_mov_b32_e32 v97, v95
	v_pk_add_f32 v[94:95], v[104:105], v[96:97]
	v_pk_mul_f32 v[96:97], v[36:37], v[36:37]
	v_pk_mul_f32 v[104:105], v[34:35], v[34:35]
	v_pk_add_f32 v[94:95], v[94:95], v[94:95] op_sel:[0,1] op_sel_hi:[1,0]
	v_pk_mov_b32 v[106:107], v[104:105], v[96:97] op_sel:[1,0]
	v_mov_b32_e32 v105, v97
	v_pk_add_f32 v[96:97], v[106:107], v[104:105]
	v_mul_f32_e32 v104, v50, v50
	v_mul_f32_e32 v105, v51, v51
	v_pk_add_f32 v[96:97], v[96:97], v[96:97] op_sel:[0,1] op_sel_hi:[1,0]
	v_mov_b32_e32 v95, v104
	v_mov_b32_e32 v97, v105
	v_pk_add_f32 v[94:95], v[94:95], v[96:97]
	v_mul_f32_e32 v96, v43, v43
	v_mul_f32_e32 v104, v45, v45
	v_mul_f32_e32 v106, v52, v52
	v_mul_f32_e32 v107, v53, v53
	v_pk_fma_f32 v[96:97], v[42:43], v[42:43], v[96:97] op_sel_hi:[1,1,0]
	v_pk_fma_f32 v[104:105], v[44:45], v[44:45], v[104:105] op_sel_hi:[1,1,0]
	v_mov_b32_e32 v97, v106
	v_mov_b32_e32 v105, v107
	v_pk_add_f32 v[96:97], v[96:97], v[104:105]
	v_pk_mul_f32 v[104:105], v[46:47], v[46:47]
	v_pk_add_f32 v[94:95], v[94:95], v[96:97]
	v_pk_mul_f32 v[96:97], v[48:49], v[48:49]
	v_cvt_pk_bf16_f32 v201, v66, v67
	v_pk_mov_b32 v[106:107], v[104:105], v[96:97] op_sel:[1,0]
	v_mov_b32_e32 v105, v97
	v_pk_add_f32 v[96:97], v[106:107], v[104:105]
	v_pk_mul_f32 v[104:105], v[56:57], v[56:57]
	v_pk_mul_f32 v[106:107], v[54:55], v[54:55]
	v_pk_add_f32 v[96:97], v[96:97], v[96:97] op_sel:[0,1] op_sel_hi:[1,0]
	v_pk_mov_b32 v[108:109], v[106:107], v[104:105] op_sel:[1,0]
	v_mov_b32_e32 v107, v105
	v_pk_add_f32 v[104:105], v[108:109], v[106:107]
	v_mul_f32_e32 v106, v62, v62
	v_mul_f32_e32 v107, v63, v63
	v_pk_add_f32 v[104:105], v[104:105], v[104:105] op_sel:[0,1] op_sel_hi:[1,0]
	v_mov_b32_e32 v97, v106
	v_mov_b32_e32 v105, v107
	v_pk_add_f32 v[96:97], v[96:97], v[104:105]
	v_mul_f32_e32 v104, v59, v59
	v_mul_f32_e32 v106, v61, v61
	v_mul_f32_e32 v108, v64, v64
	v_mul_f32_e32 v109, v65, v65
	v_pk_fma_f32 v[104:105], v[58:59], v[58:59], v[104:105] op_sel_hi:[1,1,0]
	v_pk_fma_f32 v[106:107], v[60:61], v[60:61], v[106:107] op_sel_hi:[1,1,0]
	v_mov_b32_e32 v105, v108
	v_mov_b32_e32 v107, v109
	v_pk_add_f32 v[104:105], v[104:105], v[106:107]
	v_lshl_add_u64 v[78:79], v[88:89], 0, s[0:1]
	v_pk_add_f32 v[96:97], v[96:97], v[104:105]
	v_mov_b32_e32 v105, v94
	v_mov_b32_e32 v104, v96
	v_mov_b32_e32 v94, v97
	v_pk_add_f32 v[104:105], v[104:105], v[94:95]
	ds_bpermute_b32 v107, v1, v105
	ds_bpermute_b32 v106, v1, v104
	v_pk_mul_f32 v[66:67], v[92:93], v[24:25] op_sel_hi:[0,1]
	v_pk_mul_f32 v[68:69], v[92:93], v[22:23] op_sel_hi:[0,1]
	v_pk_mul_f32 v[68:69], v[6:7], v[68:69]
	v_pk_mul_f32 v[66:67], v[8:9], v[66:67]
	v_pk_fma_f32 v[68:69], v[76:77], v[68:69], v[82:83]
	v_pk_fma_f32 v[66:67], v[74:75], v[66:67], v[84:85]
	s_waitcnt lgkmcnt(0)
; #define LAS __attribute__((address_space(3)))
; __device__ __forceinline__ unsigned pk2(float lo, float hi) { const f32x2cv v = {lo, hi}; const bf16x2cv b = __builtin_convertvector(v, bf16x2cv); return __builtin_bit_cast(unsigned, b); }
; __device__ __forceinline__ float shx(float v, int o, int lane) { return __builtin_bit_cast(float, __builtin_amdgcn_ds_bpermute((lane ^ o) << 2, __builtin_bit_cast(int, v))); }
; __global__ void __launch_bounds__(NT, 2) fwd_kernel(Args args) {
;     ...
;             for (int q = 0; q < 4; ++q) { if (q < nr) { const int m = (grp < 2) ? 64 * bl + 8 * wave + 4 * grp + q : MLAT + 4 * bl + wave; float ss = 0.f;
; #pragma unroll
;                 for (int j = 0; j < 4; ++j) ss += (v[q][j].x * v[q][j].x + v[q][j].y * v[q][j].y) + (v[q][j].z * v[q][j].z + v[q][j].w * v[q][j].w);
; #pragma unroll
;                 for (int o = 1; o < 64; o <<= 1) ss += shx(ss, o, lane);
;                 const float rstd = rsqrtf(ss * (1.f / D) + EPS);
; #pragma unroll
;                 for (int j = 0; j < 4; ++j) { const int d0 = 4 * (lane + 64 * j); const f32x4 g = gpre[j];
;                     const f32x4 sh = *(LAS f32x4*)(T + toff + d0), sc = *(LAS f32x4*)(T + toff + 1024 + d0);
;                     const f32x4 h = (v[q][j] * rstd * g) * (sc + 1.0f) + sh;
;                     v2u w; w.x = pk2(h.x, h.y); w.y = pk2(h.z, h.w); *(v2u*)(H + (size_t)m * D + d0) = w; } } }
	v_pk_add_f32 v[112:113], v[104:105], v[106:107]
	v_cvt_pk_bf16_f32 v202, v68, v69
	v_cvt_pk_bf16_f32 v203, v66, v67
	ds_bpermute_b32 v115, v91, v113
	ds_bpermute_b32 v114, v91, v112
	s_nop 1
	v_mov_b32_dpp v204, v200 quad_perm:[1,0,3,2] row_mask:0xf bank_mask:0xf
	v_mov_b32_dpp v205, v201 quad_perm:[1,0,3,2] row_mask:0xf bank_mask:0xf
	v_mov_b32_dpp v206, v202 quad_perm:[1,0,3,2] row_mask:0xf bank_mask:0xf
	v_mov_b32_dpp v207, v203 quad_perm:[1,0,3,2] row_mask:0xf bank_mask:0xf
	v_lshl_add_u64 v[212:213], v[78:79], 0, v[214:215]
	v_cndmask_b32_e64 v208, v206, v200, s[98:99]
	v_cndmask_b32_e64 v209, v207, v201, s[98:99]
	v_cndmask_b32_e64 v210, v202, v204, s[98:99]
	v_cndmask_b32_e64 v211, v203, v205, s[98:99]
	global_store_dwordx4 v[212:213], v[208:211], off
	ds_read_b128 v[66:69], v103 offset:2048
	ds_read_b128 v[70:73], v103 offset:6144
	v_pk_mul_f32 v[74:75], v[92:93], v[32:33] op_sel_hi:[0,1]
	v_pk_mul_f32 v[76:77], v[92:93], v[30:31] op_sel_hi:[0,1]
	s_waitcnt lgkmcnt(2)
	v_pk_add_f32 v[112:113], v[112:113], v[114:115]
	ds_bpermute_b32 v115, v93, v113
	ds_bpermute_b32 v114, v93, v112
	v_pk_mul_f32 v[80:81], v[10:11], v[76:77]
	v_pk_mul_f32 v[82:83], v[12:13], v[74:75]
	s_waitcnt lgkmcnt(2)
	v_pk_add_f32 v[84:85], v[72:73], 1.0 op_sel_hi:[1,0]
	v_pk_add_f32 v[128:129], v[70:71], 1.0 op_sel_hi:[1,0]
	v_pk_fma_f32 v[82:83], v[84:85], v[82:83], v[68:69]
	v_pk_fma_f32 v[80:81], v[128:129], v[80:81], v[66:67]
	ds_read_b128 v[74:77], v103 offset:6144
	ds_read_b128 v[94:97], v103 offset:7168
	v_cvt_pk_bf16_f32 v200, v80, v81
	v_cvt_pk_bf16_f32 v201, v82, v83
	ds_read_b128 v[70:73], v103 offset:2048
	ds_read_b128 v[80:83], v103 offset:3072
	s_waitcnt lgkmcnt(4)
	v_pk_add_f32 v[112:113], v[112:113], v[114:115]
	ds_bpermute_b32 v115, v98, v113
	ds_bpermute_b32 v114, v98, v112
	v_pk_mul_f32 v[108:109], v[92:93], v[40:41] op_sel_hi:[0,1]
	v_pk_mul_f32 v[110:111], v[92:93], v[38:39] op_sel_hi:[0,1]
	v_pk_mul_f32 v[110:111], v[14:15], v[110:111]
	v_pk_mul_f32 v[108:109], v[16:17], v[108:109]
	s_waitcnt lgkmcnt(4)
	v_pk_add_f32 v[130:131], v[96:97], 1.0 op_sel_hi:[1,0]
	v_pk_add_f32 v[132:133], v[94:95], 1.0 op_sel_hi:[1,0]
	s_waitcnt lgkmcnt(2)
	v_pk_fma_f32 v[108:109], v[130:131], v[108:109], v[82:83]
	v_pk_fma_f32 v[110:111], v[132:133], v[110:111], v[80:81]
	ds_read_b128 v[94:97], v103 offset:3072
	v_cvt_pk_bf16_f32 v202, v110, v111
	v_cvt_pk_bf16_f32 v203, v108, v109
	s_nop 1
	v_mov_b32_dpp v204, v200 quad_perm:[1,0,3,2] row_mask:0xf bank_mask:0xf
	v_mov_b32_dpp v205, v201 quad_perm:[1,0,3,2] row_mask:0xf bank_mask:0xf
	v_mov_b32_dpp v206, v202 quad_perm:[1,0,3,2] row_mask:0xf bank_mask:0xf
	v_mov_b32_dpp v207, v203 quad_perm:[1,0,3,2] row_mask:0xf bank_mask:0xf
	v_lshl_add_u64 v[212:213], v[78:79], 0, v[214:215]
	v_cndmask_b32_e64 v208, v206, v200, s[98:99]
	v_cndmask_b32_e64 v209, v207, v201, s[98:99]
	v_cndmask_b32_e64 v210, v202, v204, s[98:99]
	v_cndmask_b32_e64 v211, v203, v205, s[98:99]
	global_store_dwordx4 v[212:213], v[208:211], off offset:1024
	s_waitcnt lgkmcnt(1)
	v_pk_add_f32 v[78:79], v[112:113], v[114:115]
	ds_bpermute_b32 v121, v99, v79
	ds_bpermute_b32 v120, v99, v78
	ds_read_b128 v[108:111], v103 offset:4096
	ds_read_b128 v[104:107], v103 offset:7168
	ds_read_b128 v[112:115], v103
	ds_read_b128 v[116:119], v103 offset:4096
	s_add_i32 s0, s20, 2
	s_waitcnt lgkmcnt(4)
	v_pk_add_f32 v[78:79], v[78:79], v[120:121]
	ds_bpermute_b32 v125, v100, v79
	ds_bpermute_b32 v124, v100, v78
	s_waitcnt lgkmcnt(5)
	v_pk_add_f32 v[134:135], v[110:111], 1.0 op_sel_hi:[1,0]
	v_pk_add_f32 v[136:137], v[108:109], 1.0 op_sel_hi:[1,0]
	ds_read_b128 v[108:111], v103 offset:1024
	ds_read_b128 v[120:123], v103 offset:5120
	s_ashr_i32 s1, s0, 31
	s_waitcnt lgkmcnt(2)
	v_pk_add_f32 v[78:79], v[78:79], v[124:125]
	s_lshl_b64 s[0:1], s[0:1], 11
	v_pk_fma_f32 v[78:79], v[78:79], s[18:19], v[90:91] op_sel_hi:[1,0,0]
	s_waitcnt lgkmcnt(0)
; #define LAS __attribute__((address_space(3)))
; __device__ __forceinline__ unsigned pk2(float lo, float hi) { const f32x2cv v = {lo, hi}; const bf16x2cv b = __builtin_convertvector(v, bf16x2cv); return __builtin_bit_cast(unsigned, b); }
; __device__ __forceinline__ float shx(float v, int o, int lane) { return __builtin_bit_cast(float, __builtin_amdgcn_ds_bpermute((lane ^ o) << 2, __builtin_bit_cast(int, v))); }
; __global__ void __launch_bounds__(NT, 2) fwd_kernel(Args args) {
;     ...
;             for (int q = 0; q < 4; ++q) { if (q < nr) { const int m = (grp < 2) ? 64 * bl + 8 * wave + 4 * grp + q : MLAT + 4 * bl + wave; float ss = 0.f;
; #pragma unroll
;                 for (int j = 0; j < 4; ++j) ss += (v[q][j].x * v[q][j].x + v[q][j].y * v[q][j].y) + (v[q][j].z * v[q][j].z + v[q][j].w * v[q][j].w);
; #pragma unroll
;                 for (int o = 1; o < 64; o <<= 1) ss += shx(ss, o, lane);
;                 const float rstd = rsqrtf(ss * (1.f / D) + EPS);
; #pragma unroll
;                 for (int j = 0; j < 4; ++j) { const int d0 = 4 * (lane + 64 * j); const f32x4 g = gpre[j];
;                     const f32x4 sh = *(LAS f32x4*)(T + toff + d0), sc = *(LAS f32x4*)(T + toff + 1024 + d0);
;                     const f32x4 h = (v[q][j] * rstd * g) * (sc + 1.0f) + sh;
;                     v2u w; w.x = pk2(h.x, h.y); w.y = pk2(h.z, h.w); *(v2u*)(H + (size_t)m * D + d0) = w; } } }
	v_pk_add_f32 v[140:141], v[122:123], 1.0 op_sel_hi:[1,0]
	v_mul_f32_e32 v92, 0x4b800000, v79
	v_cmp_gt_f32_e32 vcc, s28, v79
	v_pk_add_f32 v[142:143], v[120:121], 1.0 op_sel_hi:[1,0]
	v_lshl_add_u64 v[138:139], v[88:89], 0, s[0:1]
	v_cndmask_b32_e32 v79, v79, v92, vcc
	v_rsq_f32_e32 v79, v79
	ds_read_b128 v[124:127], v103 offset:5120
	s_add_i32 s0, s20, 3
	s_ashr_i32 s1, s0, 31
	v_mul_f32_e32 v92, 0x45800000, v79
	v_cndmask_b32_e32 v92, v79, v92, vcc
	v_pk_mul_f32 v[120:121], v[92:93], v[28:29] op_sel_hi:[0,1]
	v_pk_mul_f32 v[122:123], v[92:93], v[26:27] op_sel_hi:[0,1]
	v_pk_mul_f32 v[144:145], v[2:3], v[122:123]
	v_pk_mul_f32 v[146:147], v[4:5], v[120:121]
	v_pk_fma_f32 v[112:113], v[136:137], v[144:145], v[112:113]
	v_pk_fma_f32 v[114:115], v[134:135], v[146:147], v[114:115]
	v_cvt_pk_bf16_f32 v200, v112, v113
	v_cvt_pk_bf16_f32 v201, v114, v115
	v_pk_mul_f32 v[112:113], v[92:93], v[36:37] op_sel_hi:[0,1]
	v_pk_mul_f32 v[114:115], v[92:93], v[34:35] op_sel_hi:[0,1]
	v_pk_mul_f32 v[134:135], v[6:7], v[114:115]
	v_pk_mul_f32 v[136:137], v[8:9], v[112:113]
	v_pk_fma_f32 v[108:109], v[142:143], v[134:135], v[108:109]
	v_pk_fma_f32 v[110:111], v[140:141], v[136:137], v[110:111]
	v_cvt_pk_bf16_f32 v202, v108, v109
	v_cvt_pk_bf16_f32 v203, v110, v111
	s_nop 1
	v_mov_b32_dpp v204, v200 quad_perm:[1,0,3,2] row_mask:0xf bank_mask:0xf
	v_mov_b32_dpp v205, v201 quad_perm:[1,0,3,2] row_mask:0xf bank_mask:0xf
	v_mov_b32_dpp v206, v202 quad_perm:[1,0,3,2] row_mask:0xf bank_mask:0xf
	v_mov_b32_dpp v207, v203 quad_perm:[1,0,3,2] row_mask:0xf bank_mask:0xf
	v_lshl_add_u64 v[212:213], v[138:139], 0, v[214:215]
	v_cndmask_b32_e64 v208, v206, v200, s[98:99]
	v_cndmask_b32_e64 v209, v207, v201, s[98:99]
	v_cndmask_b32_e64 v210, v202, v204, s[98:99]
	v_cndmask_b32_e64 v211, v203, v205, s[98:99]
	global_store_dwordx4 v[212:213], v[208:211], off
	v_pk_mul_f32 v[108:109], v[92:93], v[44:45] op_sel_hi:[0,1]
	v_pk_mul_f32 v[110:111], v[92:93], v[42:43] op_sel_hi:[0,1]
	v_pk_mul_f32 v[110:111], v[10:11], v[110:111]
	v_pk_mul_f32 v[108:109], v[12:13], v[108:109]
	v_mul_f32_e32 v79, 0x4b800000, v78
	v_cmp_gt_f32_e32 vcc, s28, v78
	v_pk_fma_f32 v[68:69], v[84:85], v[108:109], v[68:69]
	v_pk_fma_f32 v[66:67], v[128:129], v[110:111], v[66:67]
	v_cndmask_b32_e32 v78, v78, v79, vcc
	v_cvt_pk_bf16_f32 v200, v66, v67
	v_cvt_pk_bf16_f32 v201, v68, v69
	v_rsq_f32_e32 v78, v78
	v_pk_mul_f32 v[66:67], v[92:93], v[52:53] op_sel_hi:[0,1]
	v_pk_mul_f32 v[68:69], v[92:93], v[50:51] op_sel_hi:[0,1]
	v_pk_mul_f32 v[68:69], v[14:15], v[68:69]
	v_pk_mul_f32 v[66:67], v[16:17], v[66:67]
	ds_read_b128 v[120:123], v103
	ds_read_b128 v[112:115], v103 offset:1024
	v_pk_fma_f32 v[66:67], v[130:131], v[66:67], v[82:83]
	v_pk_fma_f32 v[68:69], v[132:133], v[68:69], v[80:81]
	v_pk_add_f32 v[80:81], v[118:119], 1.0 op_sel_hi:[1,0]
	v_cvt_pk_bf16_f32 v202, v68, v69
	v_cvt_pk_bf16_f32 v203, v66, v67
	v_mul_f32_e32 v66, 0x45800000, v78
	v_cndmask_b32_e32 v66, v78, v66, vcc
	s_nop 1
	v_mov_b32_dpp v204, v200 quad_perm:[1,0,3,2] row_mask:0xf bank_mask:0xf
	v_mov_b32_dpp v205, v201 quad_perm:[1,0,3,2] row_mask:0xf bank_mask:0xf
	v_mov_b32_dpp v206, v202 quad_perm:[1,0,3,2] row_mask:0xf bank_mask:0xf
	v_mov_b32_dpp v207, v203 quad_perm:[1,0,3,2] row_mask:0xf bank_mask:0xf
	v_lshl_add_u64 v[212:213], v[138:139], 0, v[214:215]
	v_cndmask_b32_e64 v208, v206, v200, s[98:99]
	v_cndmask_b32_e64 v209, v207, v201, s[98:99]
	v_cndmask_b32_e64 v210, v202, v204, s[98:99]
	v_cndmask_b32_e64 v211, v203, v205, s[98:99]
	global_store_dwordx4 v[212:213], v[208:211], off offset:1024
	v_pk_mul_f32 v[68:69], v[66:67], v[48:49] op_sel_hi:[0,1]
	v_pk_mul_f32 v[78:79], v[66:67], v[46:47] op_sel_hi:[0,1]
	v_pk_mul_f32 v[78:79], v[2:3], v[78:79]
	v_pk_mul_f32 v[68:69], v[4:5], v[68:69]
	v_pk_add_f32 v[82:83], v[116:117], 1.0 op_sel_hi:[1,0]
	s_lshl_b64 s[0:1], s[0:1], 11
	s_waitcnt lgkmcnt(1)
	v_pk_fma_f32 v[68:69], v[80:81], v[68:69], v[122:123]
	v_pk_fma_f32 v[78:79], v[82:83], v[78:79], v[120:121]
	v_pk_mul_f32 v[80:81], v[66:67], v[54:55] op_sel_hi:[0,1]
	v_cvt_pk_bf16_f32 v200, v78, v79
	v_cvt_pk_bf16_f32 v201, v68, v69
	v_lshl_add_u64 v[68:69], v[88:89], 0, s[0:1]
	v_pk_mul_f32 v[78:79], v[66:67], v[56:57] op_sel_hi:[0,1]
	v_pk_mul_f32 v[80:81], v[6:7], v[80:81]
	v_pk_mul_f32 v[78:79], v[8:9], v[78:79]
	v_pk_add_f32 v[82:83], v[126:127], 1.0 op_sel_hi:[1,0]
	v_pk_add_f32 v[84:85], v[124:125], 1.0 op_sel_hi:[1,0]
	s_waitcnt lgkmcnt(0)
	v_pk_fma_f32 v[78:79], v[82:83], v[78:79], v[114:115]
	v_pk_fma_f32 v[80:81], v[84:85], v[80:81], v[112:113]
	v_pk_add_f32 v[76:77], v[76:77], 1.0 op_sel_hi:[1,0]
	v_cvt_pk_bf16_f32 v202, v80, v81
	v_cvt_pk_bf16_f32 v203, v78, v79
	s_nop 1
	v_mov_b32_dpp v204, v200 quad_perm:[1,0,3,2] row_mask:0xf bank_mask:0xf
	v_mov_b32_dpp v205, v201 quad_perm:[1,0,3,2] row_mask:0xf bank_mask:0xf
	v_mov_b32_dpp v206, v202 quad_perm:[1,0,3,2] row_mask:0xf bank_mask:0xf
	v_mov_b32_dpp v207, v203 quad_perm:[1,0,3,2] row_mask:0xf bank_mask:0xf
	v_lshl_add_u64 v[212:213], v[68:69], 0, v[214:215]
	v_cndmask_b32_e64 v208, v206, v200, s[98:99]
	v_cndmask_b32_e64 v209, v207, v201, s[98:99]
	v_cndmask_b32_e64 v210, v202, v204, s[98:99]
	v_cndmask_b32_e64 v211, v203, v205, s[98:99]
	global_store_dwordx4 v[212:213], v[208:211], off
	v_pk_mul_f32 v[78:79], v[66:67], v[60:61] op_sel_hi:[0,1]
	v_pk_mul_f32 v[80:81], v[66:67], v[58:59] op_sel_hi:[0,1]
	v_pk_mul_f32 v[80:81], v[10:11], v[80:81]
	v_pk_mul_f32 v[78:79], v[12:13], v[78:79]
	v_pk_add_f32 v[74:75], v[74:75], 1.0 op_sel_hi:[1,0]
	v_pk_fma_f32 v[72:73], v[76:77], v[78:79], v[72:73]
	v_pk_fma_f32 v[70:71], v[74:75], v[80:81], v[70:71]
	v_pk_add_f32 v[74:75], v[104:105], 1.0 op_sel_hi:[1,0]
	v_cvt_pk_bf16_f32 v200, v70, v71
	v_cvt_pk_bf16_f32 v201, v72, v73
	v_pk_mul_f32 v[70:71], v[66:67], v[64:65] op_sel_hi:[0,1]
	v_pk_mul_f32 v[66:67], v[66:67], v[62:63] op_sel_hi:[0,1]
	v_pk_mul_f32 v[66:67], v[14:15], v[66:67]
	v_pk_mul_f32 v[70:71], v[16:17], v[70:71]
	v_pk_add_f32 v[72:73], v[106:107], 1.0 op_sel_hi:[1,0]
	v_pk_fma_f32 v[66:67], v[74:75], v[66:67], v[94:95]
	v_pk_fma_f32 v[70:71], v[72:73], v[70:71], v[96:97]
	v_cvt_pk_bf16_f32 v202, v66, v67
	v_cvt_pk_bf16_f32 v203, v70, v71
	s_nop 1
	v_mov_b32_dpp v204, v200 quad_perm:[1,0,3,2] row_mask:0xf bank_mask:0xf
	v_mov_b32_dpp v205, v201 quad_perm:[1,0,3,2] row_mask:0xf bank_mask:0xf
	v_mov_b32_dpp v206, v202 quad_perm:[1,0,3,2] row_mask:0xf bank_mask:0xf
	v_mov_b32_dpp v207, v203 quad_perm:[1,0,3,2] row_mask:0xf bank_mask:0xf
	v_lshl_add_u64 v[212:213], v[68:69], 0, v[214:215]
	v_cndmask_b32_e64 v208, v206, v200, s[98:99]
	v_cndmask_b32_e64 v209, v207, v201, s[98:99]
	v_cndmask_b32_e64 v210, v202, v204, s[98:99]
	v_cndmask_b32_e64 v211, v203, v205, s[98:99]
	global_store_dwordx4 v[212:213], v[208:211], off offset:1024
	s_branch .LBB0_100
